# scan loop: alternate wave priority with s_setprio (V waves high in first half-step, O waves high in second half-step)
# baseline (speedup 1.0000x reference)
.Lscan_V_loop:
	s_setprio 1
	s_waitcnt vmcnt(14)
	ds_read_b128 v[32:35], v8 offset:0
	ds_read_b128 v[36:39], v8 offset:4352
	ds_read_b128 v[40:43], v8 offset:64
	ds_read_b128 v[44:47], v8 offset:4416
	ds_read_b128 v[48:51], v8 offset:128
	ds_read_b128 v[52:55], v8 offset:4480
	ds_read_b128 v[56:59], v8 offset:192
	ds_read_b128 v[60:63], v8 offset:4544
	global_load_dwordx4 v[136:139], v1, s[0:1]
	global_load_dwordx4 v[140:143], v1, s[0:1] offset:1024
	s_waitcnt vmcnt(11)
	v_mul_f32_e32 v16, v184, v16
	v_mul_f32_e32 v17, v184, v17
	v_mul_f32_e32 v18, v184, v18
	v_mul_f32_e32 v19, v184, v19
	global_load_dwordx4 v[144:147], v1, s[0:1] offset:2048
	v_mul_f32_e32 v20, v184, v20
	v_mul_f32_e32 v21, v184, v21
	v_mul_f32_e32 v22, v184, v22
	v_mul_f32_e32 v23, v184, v23
	v_lshlrev_b32_e32 v64, 16, v88
	v_and_b32_e32 v65, 0xffff0000, v88
	v_lshlrev_b32_e32 v66, 16, v89
	v_and_b32_e32 v67, 0xffff0000, v89
	v_lshlrev_b32_e32 v68, 16, v90
	v_and_b32_e32 v69, 0xffff0000, v90
	v_lshlrev_b32_e32 v70, 16, v91
	v_and_b32_e32 v71, 0xffff0000, v91
	global_load_dwordx4 v[148:151], v1, s[0:1] offset:3072
	s_waitcnt lgkmcnt(6)
	v_mfma_f32_16x16x32_bf16 v[24:27], v[72:75], v[32:35], 0
	v_mfma_f32_16x16x32_bf16 v[28:31], v[72:75], v[36:39], 0
	global_load_dwordx2 v[188:189], v2, s[2:3]
	s_waitcnt lgkmcnt(4)
	v_mfma_f32_16x16x32_bf16 v[24:27], v[76:79], v[40:43], v[24:27]
	v_mfma_f32_16x16x32_bf16 v[28:31], v[76:79], v[44:47], v[28:31]
	global_load_dwordx2 v[190:191], v2, s[2:3] offset:2048
	s_waitcnt lgkmcnt(2)
	v_mfma_f32_16x16x32_bf16 v[24:27], v[80:83], v[48:51], v[24:27]
	v_mfma_f32_16x16x32_bf16 v[28:31], v[80:83], v[52:55], v[28:31]
	global_load_dwordx4 v[196:199], v1, s[4:5]
	s_waitcnt lgkmcnt(0)
	v_mfma_f32_16x16x32_bf16 v[24:27], v[84:87], v[56:59], v[24:27]
	v_mfma_f32_16x16x32_bf16 v[28:31], v[84:87], v[60:63], v[28:31]
	global_load_dwordx4 v[200:203], v1, s[4:5] offset:1024
	global_load_dword v186, v3, s[6:7]
	v_add_u32_e32 v1, 0x4000, v1
	v_add_u32_e32 v2, 0x4000, v2
	v_add_u32_e32 v3, 4, v3
	s_nop 2
	v_sub_f32_e32 v64, v64, v24
	v_sub_f32_e32 v65, v65, v25
	v_sub_f32_e32 v66, v66, v26
	v_sub_f32_e32 v67, v67, v27
	v_sub_f32_e32 v68, v68, v28
	v_sub_f32_e32 v69, v69, v29
	v_sub_f32_e32 v70, v70, v30
	v_sub_f32_e32 v71, v71, v31
	v_cvt_pk_bf16_f32 v64, v64, v65
	v_cvt_pk_bf16_f32 v65, v66, v67
	v_cvt_pk_bf16_f32 v68, v68, v69
	v_cvt_pk_bf16_f32 v69, v70, v71
	ds_write_b64 v10, v[64:65] offset:17408
	ds_write_b64 v10, v[68:69] offset:19712
	s_waitcnt lgkmcnt(0)
	s_barrier
	s_setprio 0
	ds_read_b128 v[32:35], v9 offset:17408
	ds_read_b128 v[36:39], v9 offset:19712
	ds_read_b128 v[40:43], v9 offset:17472
	ds_read_b128 v[44:47], v9 offset:19776
	s_waitcnt lgkmcnt(2)
	v_mfma_f32_16x16x32_bf16 v[16:19], v[96:99], v[32:35], v[16:19]
	v_mfma_f32_16x16x32_bf16 v[20:23], v[96:99], v[36:39], v[20:23]
	s_waitcnt lgkmcnt(0)
	v_mfma_f32_16x16x32_bf16 v[16:19], v[100:103], v[40:43], v[16:19]
	v_mfma_f32_16x16x32_bf16 v[20:23], v[100:103], v[44:47], v[20:23]
	s_nop 7
	v_cvt_pk_bf16_f32 v64, v16, v17
	v_cvt_pk_bf16_f32 v65, v18, v19
	v_cvt_pk_bf16_f32 v66, v20, v21
	v_cvt_pk_bf16_f32 v67, v22, v23
	ds_write_b64 v11, v[64:65] offset:8704
	ds_write_b64 v11, v[66:67] offset:13056
	s_waitcnt lgkmcnt(0)
	s_barrier
	s_setprio 1
	s_waitcnt vmcnt(14)
	ds_read_b128 v[32:35], v8 offset:8704
	ds_read_b128 v[36:39], v8 offset:13056
	ds_read_b128 v[40:43], v8 offset:8768
	ds_read_b128 v[44:47], v8 offset:13120
	ds_read_b128 v[48:51], v8 offset:8832
	ds_read_b128 v[52:55], v8 offset:13184
	ds_read_b128 v[56:59], v8 offset:8896
	ds_read_b128 v[60:63], v8 offset:13248
	global_load_dwordx4 v[216:219], v1, s[0:1]
	global_load_dwordx4 v[220:223], v1, s[0:1] offset:1024
	s_waitcnt vmcnt(11)
	v_mul_f32_e32 v16, v185, v16
	v_mul_f32_e32 v17, v185, v17
	v_mul_f32_e32 v18, v185, v18
	v_mul_f32_e32 v19, v185, v19
	global_load_dwordx4 v[224:227], v1, s[0:1] offset:2048
	v_mul_f32_e32 v20, v185, v20
	v_mul_f32_e32 v21, v185, v21
	v_mul_f32_e32 v22, v185, v22
	v_mul_f32_e32 v23, v185, v23
	v_lshlrev_b32_e32 v64, 16, v120
	v_and_b32_e32 v65, 0xffff0000, v120
	v_lshlrev_b32_e32 v66, 16, v121
	v_and_b32_e32 v67, 0xffff0000, v121
	v_lshlrev_b32_e32 v68, 16, v122
	v_and_b32_e32 v69, 0xffff0000, v122
	v_lshlrev_b32_e32 v70, 16, v123
	v_and_b32_e32 v71, 0xffff0000, v123
	global_load_dwordx4 v[228:231], v1, s[0:1] offset:3072
	s_waitcnt lgkmcnt(6)
	v_mfma_f32_16x16x32_bf16 v[24:27], v[104:107], v[32:35], 0
	v_mfma_f32_16x16x32_bf16 v[28:31], v[104:107], v[36:39], 0
	global_load_dwordx2 v[232:233], v2, s[2:3]
	s_waitcnt lgkmcnt(4)
	v_mfma_f32_16x16x32_bf16 v[24:27], v[108:111], v[40:43], v[24:27]
	v_mfma_f32_16x16x32_bf16 v[28:31], v[108:111], v[44:47], v[28:31]
	global_load_dwordx2 v[234:235], v2, s[2:3] offset:2048
	s_waitcnt lgkmcnt(2)
	v_mfma_f32_16x16x32_bf16 v[24:27], v[112:115], v[48:51], v[24:27]
	v_mfma_f32_16x16x32_bf16 v[28:31], v[112:115], v[52:55], v[28:31]
	global_load_dwordx4 v[240:243], v1, s[4:5]
	s_waitcnt lgkmcnt(0)
	v_mfma_f32_16x16x32_bf16 v[24:27], v[116:119], v[56:59], v[24:27]
	v_mfma_f32_16x16x32_bf16 v[28:31], v[116:119], v[60:63], v[28:31]
	global_load_dwordx4 v[244:247], v1, s[4:5] offset:1024
	global_load_dword v187, v3, s[6:7]
	v_add_u32_e32 v1, 0x4000, v1
	v_add_u32_e32 v2, 0x4000, v2
	v_add_u32_e32 v3, 4, v3
	s_nop 2
	v_sub_f32_e32 v64, v64, v24
	v_sub_f32_e32 v65, v65, v25
	v_sub_f32_e32 v66, v66, v26
	v_sub_f32_e32 v67, v67, v27
	v_sub_f32_e32 v68, v68, v28
	v_sub_f32_e32 v69, v69, v29
	v_sub_f32_e32 v70, v70, v30
	v_sub_f32_e32 v71, v71, v31
	v_cvt_pk_bf16_f32 v64, v64, v65
	v_cvt_pk_bf16_f32 v65, v66, v67
	v_cvt_pk_bf16_f32 v68, v68, v69
	v_cvt_pk_bf16_f32 v69, v70, v71
	ds_write_b64 v10, v[64:65] offset:17408
	ds_write_b64 v10, v[68:69] offset:19712
	s_waitcnt lgkmcnt(0)
	s_barrier
	s_setprio 0
	ds_read_b128 v[32:35], v9 offset:17408
	ds_read_b128 v[36:39], v9 offset:19712
	ds_read_b128 v[40:43], v9 offset:17472
	ds_read_b128 v[44:47], v9 offset:19776
	s_waitcnt lgkmcnt(2)
	v_mfma_f32_16x16x32_bf16 v[16:19], v[128:131], v[32:35], v[16:19]
	v_mfma_f32_16x16x32_bf16 v[20:23], v[128:131], v[36:39], v[20:23]
	s_waitcnt lgkmcnt(0)
	v_mfma_f32_16x16x32_bf16 v[16:19], v[132:135], v[40:43], v[16:19]
	v_mfma_f32_16x16x32_bf16 v[20:23], v[132:135], v[44:47], v[20:23]
	s_nop 7
	v_cvt_pk_bf16_f32 v64, v16, v17
	v_cvt_pk_bf16_f32 v65, v18, v19
	v_cvt_pk_bf16_f32 v66, v20, v21
	v_cvt_pk_bf16_f32 v67, v22, v23
	ds_write_b64 v11, v[64:65] offset:0
	ds_write_b64 v11, v[66:67] offset:4352
	s_waitcnt lgkmcnt(0)
	s_barrier
	s_setprio 1
	s_waitcnt vmcnt(14)
	ds_read_b128 v[32:35], v8 offset:0
	ds_read_b128 v[36:39], v8 offset:4352
	ds_read_b128 v[40:43], v8 offset:64
	ds_read_b128 v[44:47], v8 offset:4416
	ds_read_b128 v[48:51], v8 offset:128
	ds_read_b128 v[52:55], v8 offset:4480
	ds_read_b128 v[56:59], v8 offset:192
	ds_read_b128 v[60:63], v8 offset:4544
	global_load_dwordx4 v[72:75], v1, s[0:1]
	global_load_dwordx4 v[76:79], v1, s[0:1] offset:1024
	s_waitcnt vmcnt(11)
	v_mul_f32_e32 v16, v186, v16
	v_mul_f32_e32 v17, v186, v17
	v_mul_f32_e32 v18, v186, v18
	v_mul_f32_e32 v19, v186, v19
	global_load_dwordx4 v[80:83], v1, s[0:1] offset:2048
	v_mul_f32_e32 v20, v186, v20
	v_mul_f32_e32 v21, v186, v21
	v_mul_f32_e32 v22, v186, v22
	v_mul_f32_e32 v23, v186, v23
	v_lshlrev_b32_e32 v64, 16, v188
	v_and_b32_e32 v65, 0xffff0000, v188
	v_lshlrev_b32_e32 v66, 16, v189
	v_and_b32_e32 v67, 0xffff0000, v189
	v_lshlrev_b32_e32 v68, 16, v190
	v_and_b32_e32 v69, 0xffff0000, v190
	v_lshlrev_b32_e32 v70, 16, v191
	v_and_b32_e32 v71, 0xffff0000, v191
	global_load_dwordx4 v[84:87], v1, s[0:1] offset:3072
	s_waitcnt lgkmcnt(6)
	v_mfma_f32_16x16x32_bf16 v[24:27], v[136:139], v[32:35], 0
	v_mfma_f32_16x16x32_bf16 v[28:31], v[136:139], v[36:39], 0
	global_load_dwordx2 v[88:89], v2, s[2:3]
	s_waitcnt lgkmcnt(4)
	v_mfma_f32_16x16x32_bf16 v[24:27], v[140:143], v[40:43], v[24:27]
	v_mfma_f32_16x16x32_bf16 v[28:31], v[140:143], v[44:47], v[28:31]
	global_load_dwordx2 v[90:91], v2, s[2:3] offset:2048
	s_waitcnt lgkmcnt(2)
	v_mfma_f32_16x16x32_bf16 v[24:27], v[144:147], v[48:51], v[24:27]
	v_mfma_f32_16x16x32_bf16 v[28:31], v[144:147], v[52:55], v[28:31]
	global_load_dwordx4 v[96:99], v1, s[4:5]
	s_waitcnt lgkmcnt(0)
	v_mfma_f32_16x16x32_bf16 v[24:27], v[148:151], v[56:59], v[24:27]
	v_mfma_f32_16x16x32_bf16 v[28:31], v[148:151], v[60:63], v[28:31]
	global_load_dwordx4 v[100:103], v1, s[4:5] offset:1024
	global_load_dword v184, v3, s[6:7]
	v_add_u32_e32 v1, 0x4000, v1
	v_add_u32_e32 v2, 0x4000, v2
	v_add_u32_e32 v3, 4, v3
	s_nop 2
	v_sub_f32_e32 v64, v64, v24
	v_sub_f32_e32 v65, v65, v25
	v_sub_f32_e32 v66, v66, v26
	v_sub_f32_e32 v67, v67, v27
	v_sub_f32_e32 v68, v68, v28
	v_sub_f32_e32 v69, v69, v29
	v_sub_f32_e32 v70, v70, v30
	v_sub_f32_e32 v71, v71, v31
	v_cvt_pk_bf16_f32 v64, v64, v65
	v_cvt_pk_bf16_f32 v65, v66, v67
	v_cvt_pk_bf16_f32 v68, v68, v69
	v_cvt_pk_bf16_f32 v69, v70, v71
	ds_write_b64 v10, v[64:65] offset:17408
	ds_write_b64 v10, v[68:69] offset:19712
	s_waitcnt lgkmcnt(0)
	s_barrier
	s_setprio 0
	ds_read_b128 v[32:35], v9 offset:17408
	ds_read_b128 v[36:39], v9 offset:19712
	ds_read_b128 v[40:43], v9 offset:17472
	ds_read_b128 v[44:47], v9 offset:19776
	s_waitcnt lgkmcnt(2)
	v_mfma_f32_16x16x32_bf16 v[16:19], v[196:199], v[32:35], v[16:19]
	v_mfma_f32_16x16x32_bf16 v[20:23], v[196:199], v[36:39], v[20:23]
	s_waitcnt lgkmcnt(0)
	v_mfma_f32_16x16x32_bf16 v[16:19], v[200:203], v[40:43], v[16:19]
	v_mfma_f32_16x16x32_bf16 v[20:23], v[200:203], v[44:47], v[20:23]
	s_nop 7
	v_cvt_pk_bf16_f32 v64, v16, v17
	v_cvt_pk_bf16_f32 v65, v18, v19
	v_cvt_pk_bf16_f32 v66, v20, v21
	v_cvt_pk_bf16_f32 v67, v22, v23
	ds_write_b64 v11, v[64:65] offset:8704
	ds_write_b64 v11, v[66:67] offset:13056
	s_waitcnt lgkmcnt(0)
	s_barrier
	s_setprio 1
	s_waitcnt vmcnt(14)
	ds_read_b128 v[32:35], v8 offset:8704
	ds_read_b128 v[36:39], v8 offset:13056
	ds_read_b128 v[40:43], v8 offset:8768
	ds_read_b128 v[44:47], v8 offset:13120
	ds_read_b128 v[48:51], v8 offset:8832
	ds_read_b128 v[52:55], v8 offset:13184
	ds_read_b128 v[56:59], v8 offset:8896
	ds_read_b128 v[60:63], v8 offset:13248
	global_load_dwordx4 v[104:107], v1, s[0:1]
	global_load_dwordx4 v[108:111], v1, s[0:1] offset:1024
	s_waitcnt vmcnt(11)
	v_mul_f32_e32 v16, v187, v16
	v_mul_f32_e32 v17, v187, v17
	v_mul_f32_e32 v18, v187, v18
	v_mul_f32_e32 v19, v187, v19
	global_load_dwordx4 v[112:115], v1, s[0:1] offset:2048
	v_mul_f32_e32 v20, v187, v20
	v_mul_f32_e32 v21, v187, v21
	v_mul_f32_e32 v22, v187, v22
	v_mul_f32_e32 v23, v187, v23
	v_lshlrev_b32_e32 v64, 16, v232
	v_and_b32_e32 v65, 0xffff0000, v232
	v_lshlrev_b32_e32 v66, 16, v233
	v_and_b32_e32 v67, 0xffff0000, v233
	v_lshlrev_b32_e32 v68, 16, v234
	v_and_b32_e32 v69, 0xffff0000, v234
	v_lshlrev_b32_e32 v70, 16, v235
	v_and_b32_e32 v71, 0xffff0000, v235
	global_load_dwordx4 v[116:119], v1, s[0:1] offset:3072
	s_waitcnt lgkmcnt(6)
	v_mfma_f32_16x16x32_bf16 v[24:27], v[216:219], v[32:35], 0
	v_mfma_f32_16x16x32_bf16 v[28:31], v[216:219], v[36:39], 0
	global_load_dwordx2 v[120:121], v2, s[2:3]
	s_waitcnt lgkmcnt(4)
	v_mfma_f32_16x16x32_bf16 v[24:27], v[220:223], v[40:43], v[24:27]
	v_mfma_f32_16x16x32_bf16 v[28:31], v[220:223], v[44:47], v[28:31]
	global_load_dwordx2 v[122:123], v2, s[2:3] offset:2048
	s_waitcnt lgkmcnt(2)
	v_mfma_f32_16x16x32_bf16 v[24:27], v[224:227], v[48:51], v[24:27]
	v_mfma_f32_16x16x32_bf16 v[28:31], v[224:227], v[52:55], v[28:31]
	global_load_dwordx4 v[128:131], v1, s[4:5]
	s_waitcnt lgkmcnt(0)
	v_mfma_f32_16x16x32_bf16 v[24:27], v[228:231], v[56:59], v[24:27]
	v_mfma_f32_16x16x32_bf16 v[28:31], v[228:231], v[60:63], v[28:31]
	global_load_dwordx4 v[132:135], v1, s[4:5] offset:1024
	global_load_dword v185, v3, s[6:7]
	v_add_u32_e32 v1, 0x4000, v1
	v_add_u32_e32 v2, 0x4000, v2
	v_add_u32_e32 v3, 4, v3
	s_nop 2
	v_sub_f32_e32 v64, v64, v24
	v_sub_f32_e32 v65, v65, v25
	v_sub_f32_e32 v66, v66, v26
	v_sub_f32_e32 v67, v67, v27
	v_sub_f32_e32 v68, v68, v28
	v_sub_f32_e32 v69, v69, v29
	v_sub_f32_e32 v70, v70, v30
	v_sub_f32_e32 v71, v71, v31
	v_cvt_pk_bf16_f32 v64, v64, v65
	v_cvt_pk_bf16_f32 v65, v66, v67
	v_cvt_pk_bf16_f32 v68, v68, v69
	v_cvt_pk_bf16_f32 v69, v70, v71
	ds_write_b64 v10, v[64:65] offset:17408
	ds_write_b64 v10, v[68:69] offset:19712
	s_waitcnt lgkmcnt(0)
	s_barrier
	s_setprio 0
	ds_read_b128 v[32:35], v9 offset:17408
	ds_read_b128 v[36:39], v9 offset:19712
	ds_read_b128 v[40:43], v9 offset:17472
	ds_read_b128 v[44:47], v9 offset:19776
	s_waitcnt lgkmcnt(2)
	v_mfma_f32_16x16x32_bf16 v[16:19], v[240:243], v[32:35], v[16:19]
	v_mfma_f32_16x16x32_bf16 v[20:23], v[240:243], v[36:39], v[20:23]
	s_waitcnt lgkmcnt(0)
	v_mfma_f32_16x16x32_bf16 v[16:19], v[244:247], v[40:43], v[16:19]
	v_mfma_f32_16x16x32_bf16 v[20:23], v[244:247], v[44:47], v[20:23]
	s_nop 7
	v_cvt_pk_bf16_f32 v64, v16, v17
	v_cvt_pk_bf16_f32 v65, v18, v19
	v_cvt_pk_bf16_f32 v66, v20, v21
	v_cvt_pk_bf16_f32 v67, v22, v23
	ds_write_b64 v11, v[64:65] offset:0
	ds_write_b64 v11, v[66:67] offset:4352
	s_waitcnt lgkmcnt(0)
	s_barrier
	s_sub_u32 s10, s10, 1
	s_cmp_lg_u32 s10, 0
	s_cbranch_scc1 .Lscan_V_loop
	s_branch .Lscan_done

.Lscan_O_loop:
	s_waitcnt vmcnt(16)
	ds_read_b128 v[32:35], v8 offset:0
	ds_read_b128 v[36:39], v8 offset:4352
	ds_read_b128 v[40:43], v8 offset:64
	ds_read_b128 v[44:47], v8 offset:4416
	ds_read_b128 v[48:51], v8 offset:128
	ds_read_b128 v[52:55], v8 offset:4480
	ds_read_b128 v[56:59], v8 offset:192
	ds_read_b128 v[60:63], v8 offset:4544
	global_load_dwordx4 v[136:139], v1, s[0:1]
	global_load_dwordx4 v[140:143], v1, s[0:1] offset:1024
	s_waitcnt vmcnt(13)
	v_mul_f32_e32 v16, v184, v16
	v_mul_f32_e32 v17, v184, v17
	v_mul_f32_e32 v18, v184, v18
	v_mul_f32_e32 v19, v184, v19
	global_load_dwordx4 v[144:147], v1, s[0:1] offset:2048
	v_mul_f32_e32 v20, v184, v20
	v_mul_f32_e32 v21, v184, v21
	v_mul_f32_e32 v22, v184, v22
	v_mul_f32_e32 v23, v184, v23
	global_load_dwordx4 v[148:151], v1, s[0:1] offset:3072
	s_waitcnt lgkmcnt(6)
	v_mfma_f32_16x16x32_bf16 v[24:27], v[72:75], v[32:35], 0
	v_mfma_f32_16x16x32_bf16 v[28:31], v[72:75], v[36:39], 0
	global_load_dwordx4 v[188:191], v2, s[2:3]
	s_waitcnt lgkmcnt(4)
	v_mfma_f32_16x16x32_bf16 v[24:27], v[76:79], v[40:43], v[24:27]
	v_mfma_f32_16x16x32_bf16 v[28:31], v[76:79], v[44:47], v[28:31]
	global_load_dwordx4 v[192:195], v2, s[2:3] offset:1024
	s_waitcnt lgkmcnt(2)
	v_mfma_f32_16x16x32_bf16 v[24:27], v[80:83], v[48:51], v[24:27]
	v_mfma_f32_16x16x32_bf16 v[28:31], v[80:83], v[52:55], v[28:31]
	global_load_dwordx4 v[196:199], v1, s[4:5]
	s_waitcnt lgkmcnt(0)
	v_mfma_f32_16x16x32_bf16 v[24:27], v[84:87], v[56:59], v[24:27]
	v_mfma_f32_16x16x32_bf16 v[28:31], v[84:87], v[60:63], v[28:31]
	global_load_dwordx4 v[200:203], v1, s[4:5] offset:1024
	global_load_dword v186, v3, s[6:7]
	v_add_u32_e32 v1, 0x4000, v1
	v_add_u32_e32 v2, 0x2000, v2
	v_add_u32_e32 v3, 4, v3
	s_waitcnt lgkmcnt(0)
	s_barrier
	s_setprio 1
	ds_read_b128 v[32:35], v9 offset:17408
	ds_read_b128 v[36:39], v9 offset:19712
	ds_read_b128 v[40:43], v9 offset:17472
	ds_read_b128 v[44:47], v9 offset:19776
	s_waitcnt lgkmcnt(2)
	v_mfma_f32_16x16x32_bf16 v[16:19], v[96:99], v[32:35], v[16:19]
	v_mfma_f32_16x16x32_bf16 v[20:23], v[96:99], v[36:39], v[20:23]
	v_mfma_f32_16x16x32_bf16 v[24:27], v[88:91], v[32:35], v[24:27]
	v_mfma_f32_16x16x32_bf16 v[28:31], v[88:91], v[36:39], v[28:31]
	s_waitcnt lgkmcnt(0)
	v_mfma_f32_16x16x32_bf16 v[16:19], v[100:103], v[40:43], v[16:19]
	v_mfma_f32_16x16x32_bf16 v[20:23], v[100:103], v[44:47], v[20:23]
	v_mfma_f32_16x16x32_bf16 v[24:27], v[92:95], v[40:43], v[24:27]
	v_mfma_f32_16x16x32_bf16 v[28:31], v[92:95], v[44:47], v[28:31]
	s_nop 5
	v_cvt_pk_bf16_f32 v64, v16, v17
	v_cvt_pk_bf16_f32 v65, v18, v19
	v_cvt_pk_bf16_f32 v66, v20, v21
	v_cvt_pk_bf16_f32 v67, v22, v23
	ds_write_b64 v11, v[64:65] offset:8704
	ds_write_b64 v11, v[66:67] offset:13056
	v_cvt_pk_bf16_f32 v68, v24, v25
	v_cvt_pk_bf16_f32 v69, v26, v27
	v_cvt_pk_bf16_f32 v70, v28, v29
	v_cvt_pk_bf16_f32 v71, v30, v31
	ds_write_b16 v13, v68 offset:0
	ds_write_b16_d16_hi v13, v68 offset:80
	ds_write_b16 v13, v69 offset:160
	ds_write_b16_d16_hi v13, v69 offset:240
	ds_write_b16 v13, v70 offset:32
	ds_write_b16_d16_hi v13, v70 offset:112
	ds_write_b16 v13, v71 offset:192
	ds_write_b16_d16_hi v13, v71 offset:272
	ds_read_b128 v[176:179], v172
	s_waitcnt lgkmcnt(0)
	s_barrier
	s_setprio 0
	global_store_dwordx4 v12, v[176:179], s[8:9]
	v_add_u32_e32 v12, 0x20000, v12
	s_waitcnt vmcnt(16)
	ds_read_b128 v[32:35], v8 offset:8704
	ds_read_b128 v[36:39], v8 offset:13056
	ds_read_b128 v[40:43], v8 offset:8768
	ds_read_b128 v[44:47], v8 offset:13120
	ds_read_b128 v[48:51], v8 offset:8832
	ds_read_b128 v[52:55], v8 offset:13184
	ds_read_b128 v[56:59], v8 offset:8896
	ds_read_b128 v[60:63], v8 offset:13248
	global_load_dwordx4 v[216:219], v1, s[0:1]
	global_load_dwordx4 v[220:223], v1, s[0:1] offset:1024
	s_waitcnt vmcnt(13)
	v_mul_f32_e32 v16, v185, v16
	v_mul_f32_e32 v17, v185, v17
	v_mul_f32_e32 v18, v185, v18
	v_mul_f32_e32 v19, v185, v19
	global_load_dwordx4 v[224:227], v1, s[0:1] offset:2048
	v_mul_f32_e32 v20, v185, v20
	v_mul_f32_e32 v21, v185, v21
	v_mul_f32_e32 v22, v185, v22
	v_mul_f32_e32 v23, v185, v23
	global_load_dwordx4 v[228:231], v1, s[0:1] offset:3072
	s_waitcnt lgkmcnt(6)
	v_mfma_f32_16x16x32_bf16 v[24:27], v[104:107], v[32:35], 0
	v_mfma_f32_16x16x32_bf16 v[28:31], v[104:107], v[36:39], 0
	global_load_dwordx4 v[232:235], v2, s[2:3]
	s_waitcnt lgkmcnt(4)
	v_mfma_f32_16x16x32_bf16 v[24:27], v[108:111], v[40:43], v[24:27]
	v_mfma_f32_16x16x32_bf16 v[28:31], v[108:111], v[44:47], v[28:31]
	global_load_dwordx4 v[236:239], v2, s[2:3] offset:1024
	s_waitcnt lgkmcnt(2)
	v_mfma_f32_16x16x32_bf16 v[24:27], v[112:115], v[48:51], v[24:27]
	v_mfma_f32_16x16x32_bf16 v[28:31], v[112:115], v[52:55], v[28:31]
	global_load_dwordx4 v[240:243], v1, s[4:5]
	s_waitcnt lgkmcnt(0)
	v_mfma_f32_16x16x32_bf16 v[24:27], v[116:119], v[56:59], v[24:27]
	v_mfma_f32_16x16x32_bf16 v[28:31], v[116:119], v[60:63], v[28:31]
	global_load_dwordx4 v[244:247], v1, s[4:5] offset:1024
	global_load_dword v187, v3, s[6:7]
	v_add_u32_e32 v1, 0x4000, v1
	v_add_u32_e32 v2, 0x2000, v2
	v_add_u32_e32 v3, 4, v3
	s_waitcnt lgkmcnt(0)
	s_barrier
	s_setprio 1
	ds_read_b128 v[32:35], v9 offset:17408
	ds_read_b128 v[36:39], v9 offset:19712
	ds_read_b128 v[40:43], v9 offset:17472
	ds_read_b128 v[44:47], v9 offset:19776
	s_waitcnt lgkmcnt(2)
	v_mfma_f32_16x16x32_bf16 v[16:19], v[128:131], v[32:35], v[16:19]
	v_mfma_f32_16x16x32_bf16 v[20:23], v[128:131], v[36:39], v[20:23]
	v_mfma_f32_16x16x32_bf16 v[24:27], v[120:123], v[32:35], v[24:27]
	v_mfma_f32_16x16x32_bf16 v[28:31], v[120:123], v[36:39], v[28:31]
	s_waitcnt lgkmcnt(0)
	v_mfma_f32_16x16x32_bf16 v[16:19], v[132:135], v[40:43], v[16:19]
	v_mfma_f32_16x16x32_bf16 v[20:23], v[132:135], v[44:47], v[20:23]
	v_mfma_f32_16x16x32_bf16 v[24:27], v[124:127], v[40:43], v[24:27]
	v_mfma_f32_16x16x32_bf16 v[28:31], v[124:127], v[44:47], v[28:31]
	s_nop 5
	v_cvt_pk_bf16_f32 v64, v16, v17
	v_cvt_pk_bf16_f32 v65, v18, v19
	v_cvt_pk_bf16_f32 v66, v20, v21
	v_cvt_pk_bf16_f32 v67, v22, v23
	ds_write_b64 v11, v[64:65] offset:0
	ds_write_b64 v11, v[66:67] offset:4352
	v_cvt_pk_bf16_f32 v68, v24, v25
	v_cvt_pk_bf16_f32 v69, v26, v27
	v_cvt_pk_bf16_f32 v70, v28, v29
	v_cvt_pk_bf16_f32 v71, v30, v31
	ds_write_b16 v13, v68 offset:0
	ds_write_b16_d16_hi v13, v68 offset:80
	ds_write_b16 v13, v69 offset:160
	ds_write_b16_d16_hi v13, v69 offset:240
	ds_write_b16 v13, v70 offset:32
	ds_write_b16_d16_hi v13, v70 offset:112
	ds_write_b16 v13, v71 offset:192
	ds_write_b16_d16_hi v13, v71 offset:272
	ds_read_b128 v[176:179], v172
	s_waitcnt lgkmcnt(0)
	s_barrier
	s_setprio 0
	global_store_dwordx4 v12, v[176:179], s[8:9]
	v_add_u32_e32 v12, 0x20000, v12
	s_waitcnt vmcnt(16)
	ds_read_b128 v[32:35], v8 offset:0
	ds_read_b128 v[36:39], v8 offset:4352
	ds_read_b128 v[40:43], v8 offset:64
	ds_read_b128 v[44:47], v8 offset:4416
	ds_read_b128 v[48:51], v8 offset:128
	ds_read_b128 v[52:55], v8 offset:4480
	ds_read_b128 v[56:59], v8 offset:192
	ds_read_b128 v[60:63], v8 offset:4544
	global_load_dwordx4 v[72:75], v1, s[0:1]
	global_load_dwordx4 v[76:79], v1, s[0:1] offset:1024
	s_waitcnt vmcnt(13)
	v_mul_f32_e32 v16, v186, v16
	v_mul_f32_e32 v17, v186, v17
	v_mul_f32_e32 v18, v186, v18
	v_mul_f32_e32 v19, v186, v19
	global_load_dwordx4 v[80:83], v1, s[0:1] offset:2048
	v_mul_f32_e32 v20, v186, v20
	v_mul_f32_e32 v21, v186, v21
	v_mul_f32_e32 v22, v186, v22
	v_mul_f32_e32 v23, v186, v23
	global_load_dwordx4 v[84:87], v1, s[0:1] offset:3072
	s_waitcnt lgkmcnt(6)
	v_mfma_f32_16x16x32_bf16 v[24:27], v[136:139], v[32:35], 0
	v_mfma_f32_16x16x32_bf16 v[28:31], v[136:139], v[36:39], 0
	global_load_dwordx4 v[88:91], v2, s[2:3]
	s_waitcnt lgkmcnt(4)
	v_mfma_f32_16x16x32_bf16 v[24:27], v[140:143], v[40:43], v[24:27]
	v_mfma_f32_16x16x32_bf16 v[28:31], v[140:143], v[44:47], v[28:31]
	global_load_dwordx4 v[92:95], v2, s[2:3] offset:1024
	s_waitcnt lgkmcnt(2)
	v_mfma_f32_16x16x32_bf16 v[24:27], v[144:147], v[48:51], v[24:27]
	v_mfma_f32_16x16x32_bf16 v[28:31], v[144:147], v[52:55], v[28:31]
	global_load_dwordx4 v[96:99], v1, s[4:5]
	s_waitcnt lgkmcnt(0)
	v_mfma_f32_16x16x32_bf16 v[24:27], v[148:151], v[56:59], v[24:27]
	v_mfma_f32_16x16x32_bf16 v[28:31], v[148:151], v[60:63], v[28:31]
	global_load_dwordx4 v[100:103], v1, s[4:5] offset:1024
	global_load_dword v184, v3, s[6:7]
	v_add_u32_e32 v1, 0x4000, v1
	v_add_u32_e32 v2, 0x2000, v2
	v_add_u32_e32 v3, 4, v3
	s_waitcnt lgkmcnt(0)
	s_barrier
	s_setprio 1
	ds_read_b128 v[32:35], v9 offset:17408
	ds_read_b128 v[36:39], v9 offset:19712
	ds_read_b128 v[40:43], v9 offset:17472
	ds_read_b128 v[44:47], v9 offset:19776
	s_waitcnt lgkmcnt(2)
	v_mfma_f32_16x16x32_bf16 v[16:19], v[196:199], v[32:35], v[16:19]
	v_mfma_f32_16x16x32_bf16 v[20:23], v[196:199], v[36:39], v[20:23]
	v_mfma_f32_16x16x32_bf16 v[24:27], v[188:191], v[32:35], v[24:27]
	v_mfma_f32_16x16x32_bf16 v[28:31], v[188:191], v[36:39], v[28:31]
	s_waitcnt lgkmcnt(0)
	v_mfma_f32_16x16x32_bf16 v[16:19], v[200:203], v[40:43], v[16:19]
	v_mfma_f32_16x16x32_bf16 v[20:23], v[200:203], v[44:47], v[20:23]
	v_mfma_f32_16x16x32_bf16 v[24:27], v[192:195], v[40:43], v[24:27]
	v_mfma_f32_16x16x32_bf16 v[28:31], v[192:195], v[44:47], v[28:31]
	s_nop 5
	v_cvt_pk_bf16_f32 v64, v16, v17
	v_cvt_pk_bf16_f32 v65, v18, v19
	v_cvt_pk_bf16_f32 v66, v20, v21
	v_cvt_pk_bf16_f32 v67, v22, v23
	ds_write_b64 v11, v[64:65] offset:8704
	ds_write_b64 v11, v[66:67] offset:13056
	v_cvt_pk_bf16_f32 v68, v24, v25
	v_cvt_pk_bf16_f32 v69, v26, v27
	v_cvt_pk_bf16_f32 v70, v28, v29
	v_cvt_pk_bf16_f32 v71, v30, v31
	ds_write_b16 v13, v68 offset:0
	ds_write_b16_d16_hi v13, v68 offset:80
	ds_write_b16 v13, v69 offset:160
	ds_write_b16_d16_hi v13, v69 offset:240
	ds_write_b16 v13, v70 offset:32
	ds_write_b16_d16_hi v13, v70 offset:112
	ds_write_b16 v13, v71 offset:192
	ds_write_b16_d16_hi v13, v71 offset:272
	ds_read_b128 v[176:179], v172
	s_waitcnt lgkmcnt(0)
	s_barrier
	s_setprio 0
	global_store_dwordx4 v12, v[176:179], s[8:9]
	v_add_u32_e32 v12, 0x20000, v12
	s_waitcnt vmcnt(16)
	ds_read_b128 v[32:35], v8 offset:8704
	ds_read_b128 v[36:39], v8 offset:13056
	ds_read_b128 v[40:43], v8 offset:8768
	ds_read_b128 v[44:47], v8 offset:13120
	ds_read_b128 v[48:51], v8 offset:8832
	ds_read_b128 v[52:55], v8 offset:13184
	ds_read_b128 v[56:59], v8 offset:8896
	ds_read_b128 v[60:63], v8 offset:13248
	global_load_dwordx4 v[104:107], v1, s[0:1]
	global_load_dwordx4 v[108:111], v1, s[0:1] offset:1024
	s_waitcnt vmcnt(13)
	v_mul_f32_e32 v16, v187, v16
	v_mul_f32_e32 v17, v187, v17
	v_mul_f32_e32 v18, v187, v18
	v_mul_f32_e32 v19, v187, v19
	global_load_dwordx4 v[112:115], v1, s[0:1] offset:2048
	v_mul_f32_e32 v20, v187, v20
	v_mul_f32_e32 v21, v187, v21
	v_mul_f32_e32 v22, v187, v22
	v_mul_f32_e32 v23, v187, v23
	global_load_dwordx4 v[116:119], v1, s[0:1] offset:3072
	s_waitcnt lgkmcnt(6)
	v_mfma_f32_16x16x32_bf16 v[24:27], v[216:219], v[32:35], 0
	v_mfma_f32_16x16x32_bf16 v[28:31], v[216:219], v[36:39], 0
	global_load_dwordx4 v[120:123], v2, s[2:3]
	s_waitcnt lgkmcnt(4)
	v_mfma_f32_16x16x32_bf16 v[24:27], v[220:223], v[40:43], v[24:27]
	v_mfma_f32_16x16x32_bf16 v[28:31], v[220:223], v[44:47], v[28:31]
	global_load_dwordx4 v[124:127], v2, s[2:3] offset:1024
	s_waitcnt lgkmcnt(2)
	v_mfma_f32_16x16x32_bf16 v[24:27], v[224:227], v[48:51], v[24:27]
	v_mfma_f32_16x16x32_bf16 v[28:31], v[224:227], v[52:55], v[28:31]
	global_load_dwordx4 v[128:131], v1, s[4:5]
	s_waitcnt lgkmcnt(0)
	v_mfma_f32_16x16x32_bf16 v[24:27], v[228:231], v[56:59], v[24:27]
	v_mfma_f32_16x16x32_bf16 v[28:31], v[228:231], v[60:63], v[28:31]
	global_load_dwordx4 v[132:135], v1, s[4:5] offset:1024
	global_load_dword v185, v3, s[6:7]
	v_add_u32_e32 v1, 0x4000, v1
	v_add_u32_e32 v2, 0x2000, v2
	v_add_u32_e32 v3, 4, v3
	s_waitcnt lgkmcnt(0)
	s_barrier
	s_setprio 1
	ds_read_b128 v[32:35], v9 offset:17408
	ds_read_b128 v[36:39], v9 offset:19712
	ds_read_b128 v[40:43], v9 offset:17472
	ds_read_b128 v[44:47], v9 offset:19776
	s_waitcnt lgkmcnt(2)
	v_mfma_f32_16x16x32_bf16 v[16:19], v[240:243], v[32:35], v[16:19]
	v_mfma_f32_16x16x32_bf16 v[20:23], v[240:243], v[36:39], v[20:23]
	v_mfma_f32_16x16x32_bf16 v[24:27], v[232:235], v[32:35], v[24:27]
	v_mfma_f32_16x16x32_bf16 v[28:31], v[232:235], v[36:39], v[28:31]
	s_waitcnt lgkmcnt(0)
	v_mfma_f32_16x16x32_bf16 v[16:19], v[244:247], v[40:43], v[16:19]
	v_mfma_f32_16x16x32_bf16 v[20:23], v[244:247], v[44:47], v[20:23]
	v_mfma_f32_16x16x32_bf16 v[24:27], v[236:239], v[40:43], v[24:27]
	v_mfma_f32_16x16x32_bf16 v[28:31], v[236:239], v[44:47], v[28:31]
	s_nop 5
	v_cvt_pk_bf16_f32 v64, v16, v17
	v_cvt_pk_bf16_f32 v65, v18, v19
	v_cvt_pk_bf16_f32 v66, v20, v21
	v_cvt_pk_bf16_f32 v67, v22, v23
	ds_write_b64 v11, v[64:65] offset:0
	ds_write_b64 v11, v[66:67] offset:4352
	v_cvt_pk_bf16_f32 v68, v24, v25
	v_cvt_pk_bf16_f32 v69, v26, v27
	v_cvt_pk_bf16_f32 v70, v28, v29
	v_cvt_pk_bf16_f32 v71, v30, v31
	ds_write_b16 v13, v68 offset:0
	ds_write_b16_d16_hi v13, v68 offset:80
	ds_write_b16 v13, v69 offset:160
	ds_write_b16_d16_hi v13, v69 offset:240
	ds_write_b16 v13, v70 offset:32
	ds_write_b16_d16_hi v13, v70 offset:112
	ds_write_b16 v13, v71 offset:192
	ds_write_b16_d16_hi v13, v71 offset:272
	ds_read_b128 v[176:179], v172
	s_waitcnt lgkmcnt(0)
	s_barrier
	s_setprio 0
	global_store_dwordx4 v12, v[176:179], s[8:9]
	v_add_u32_e32 v12, 0x20000, v12
	s_sub_u32 s10, s10, 1
	s_cmp_lg_u32 s10, 0
	s_cbranch_scc1 .Lscan_O_loop
	s_branch .Lscan_done

.Lscan_P_loop:
	s_waitcnt vmcnt(14)
	ds_read_b128 v[32:35], v8 offset:0
	ds_read_b128 v[36:39], v8 offset:4352
	ds_read_b128 v[40:43], v8 offset:64
	ds_read_b128 v[44:47], v8 offset:4416
	ds_read_b128 v[48:51], v8 offset:128
	ds_read_b128 v[52:55], v8 offset:4480
	ds_read_b128 v[56:59], v8 offset:192
	ds_read_b128 v[60:63], v8 offset:4544
	global_load_dwordx4 v[136:139], v1, s[0:1]
	global_load_dwordx4 v[140:143], v1, s[0:1] offset:1024
	s_waitcnt vmcnt(12)
	v_mul_f32_e32 v16, v184, v16
	v_mul_f32_e32 v17, v184, v17
	v_mul_f32_e32 v18, v184, v18
	v_mul_f32_e32 v19, v184, v19
	global_load_dwordx4 v[144:147], v1, s[0:1] offset:2048
	v_mul_f32_e32 v20, v184, v20
	v_mul_f32_e32 v21, v184, v21
	v_mul_f32_e32 v22, v184, v22
	v_mul_f32_e32 v23, v184, v23
	global_load_dwordx4 v[148:151], v1, s[0:1] offset:3072
	s_waitcnt lgkmcnt(6)
	v_mfma_f32_16x16x32_bf16 v[24:27], v[72:75], v[32:35], 0
	v_mfma_f32_16x16x32_bf16 v[28:31], v[72:75], v[36:39], 0
	global_load_dwordx4 v[188:191], v2, s[2:3]
	s_waitcnt lgkmcnt(4)
	v_mfma_f32_16x16x32_bf16 v[24:27], v[76:79], v[40:43], v[24:27]
	v_mfma_f32_16x16x32_bf16 v[28:31], v[76:79], v[44:47], v[28:31]
	global_load_dwordx4 v[196:199], v1, s[4:5]
	s_waitcnt lgkmcnt(2)
	v_mfma_f32_16x16x32_bf16 v[24:27], v[80:83], v[48:51], v[24:27]
	v_mfma_f32_16x16x32_bf16 v[28:31], v[80:83], v[52:55], v[28:31]
	global_load_dwordx4 v[200:203], v1, s[4:5] offset:1024
	s_waitcnt lgkmcnt(0)
	v_mfma_f32_16x16x32_bf16 v[24:27], v[84:87], v[56:59], v[24:27]
	v_mfma_f32_16x16x32_bf16 v[28:31], v[84:87], v[60:63], v[28:31]
	global_load_dword v186, v3, s[6:7]
	v_add_u32_e32 v1, 0x4000, v1
	v_add_u32_e32 v2, 0x2000, v2
	v_add_u32_e32 v3, 4, v3
	s_waitcnt lgkmcnt(0)
	s_barrier
	s_setprio 1
	ds_read_b128 v[32:35], v9 offset:17408
	ds_read_b128 v[36:39], v9 offset:19712
	ds_read_b128 v[40:43], v9 offset:17472
	ds_read_b128 v[44:47], v9 offset:19776
	s_waitcnt lgkmcnt(2)
	v_mfma_f32_16x16x32_bf16 v[16:19], v[96:99], v[32:35], v[16:19]
	v_mfma_f32_16x16x32_bf16 v[20:23], v[96:99], v[36:39], v[20:23]
	v_mfma_f32_16x16x32_bf16 v[24:27], v[88:91], v[32:35], v[24:27]
	v_mfma_f32_16x16x32_bf16 v[28:31], v[88:91], v[36:39], v[28:31]
	s_waitcnt lgkmcnt(0)
	v_mfma_f32_16x16x32_bf16 v[16:19], v[100:103], v[40:43], v[16:19]
	v_mfma_f32_16x16x32_bf16 v[20:23], v[100:103], v[44:47], v[20:23]
	s_nop 7
	v_cvt_pk_bf16_f32 v64, v16, v17
	v_cvt_pk_bf16_f32 v65, v18, v19
	v_cvt_pk_bf16_f32 v66, v20, v21
	v_cvt_pk_bf16_f32 v67, v22, v23
	ds_write_b64 v11, v[64:65] offset:8704
	ds_write_b64 v11, v[66:67] offset:13056
	v_cvt_pk_bf16_f32 v68, v24, v25
	v_cvt_pk_bf16_f32 v69, v26, v27
	v_cvt_pk_bf16_f32 v70, v28, v29
	v_cvt_pk_bf16_f32 v71, v30, v31
	ds_write_b16 v13, v68 offset:0
	ds_write_b16_d16_hi v13, v68 offset:80
	ds_write_b16 v13, v69 offset:160
	ds_write_b16_d16_hi v13, v69 offset:240
	ds_write_b16 v13, v70 offset:32
	ds_write_b16_d16_hi v13, v70 offset:112
	ds_write_b16 v13, v71 offset:192
	ds_write_b16_d16_hi v13, v71 offset:272
	ds_read_b128 v[176:179], v172
	s_waitcnt lgkmcnt(0)
	s_barrier
	s_setprio 0
	global_store_dwordx4 v12, v[176:179], s[8:9]
	v_add_u32_e32 v12, 0x20000, v12
	s_waitcnt vmcnt(14)
	ds_read_b128 v[32:35], v8 offset:8704
	ds_read_b128 v[36:39], v8 offset:13056
	ds_read_b128 v[40:43], v8 offset:8768
	ds_read_b128 v[44:47], v8 offset:13120
	ds_read_b128 v[48:51], v8 offset:8832
	ds_read_b128 v[52:55], v8 offset:13184
	ds_read_b128 v[56:59], v8 offset:8896
	ds_read_b128 v[60:63], v8 offset:13248
	global_load_dwordx4 v[216:219], v1, s[0:1]
	global_load_dwordx4 v[220:223], v1, s[0:1] offset:1024
	s_waitcnt vmcnt(12)
	v_mul_f32_e32 v16, v185, v16
	v_mul_f32_e32 v17, v185, v17
	v_mul_f32_e32 v18, v185, v18
	v_mul_f32_e32 v19, v185, v19
	global_load_dwordx4 v[224:227], v1, s[0:1] offset:2048
	v_mul_f32_e32 v20, v185, v20
	v_mul_f32_e32 v21, v185, v21
	v_mul_f32_e32 v22, v185, v22
	v_mul_f32_e32 v23, v185, v23
	global_load_dwordx4 v[228:231], v1, s[0:1] offset:3072
	s_waitcnt lgkmcnt(6)
	v_mfma_f32_16x16x32_bf16 v[24:27], v[104:107], v[32:35], 0
	v_mfma_f32_16x16x32_bf16 v[28:31], v[104:107], v[36:39], 0
	global_load_dwordx4 v[232:235], v2, s[2:3]
	s_waitcnt lgkmcnt(4)
	v_mfma_f32_16x16x32_bf16 v[24:27], v[108:111], v[40:43], v[24:27]
	v_mfma_f32_16x16x32_bf16 v[28:31], v[108:111], v[44:47], v[28:31]
	global_load_dwordx4 v[240:243], v1, s[4:5]
	s_waitcnt lgkmcnt(2)
	v_mfma_f32_16x16x32_bf16 v[24:27], v[112:115], v[48:51], v[24:27]
	v_mfma_f32_16x16x32_bf16 v[28:31], v[112:115], v[52:55], v[28:31]
	global_load_dwordx4 v[244:247], v1, s[4:5] offset:1024
	s_waitcnt lgkmcnt(0)
	v_mfma_f32_16x16x32_bf16 v[24:27], v[116:119], v[56:59], v[24:27]
	v_mfma_f32_16x16x32_bf16 v[28:31], v[116:119], v[60:63], v[28:31]
	global_load_dword v187, v3, s[6:7]
	v_add_u32_e32 v1, 0x4000, v1
	v_add_u32_e32 v2, 0x2000, v2
	v_add_u32_e32 v3, 4, v3
	s_waitcnt lgkmcnt(0)
	s_barrier
	s_setprio 1
	ds_read_b128 v[32:35], v9 offset:17408
	ds_read_b128 v[36:39], v9 offset:19712
	ds_read_b128 v[40:43], v9 offset:17472
	ds_read_b128 v[44:47], v9 offset:19776
	s_waitcnt lgkmcnt(2)
	v_mfma_f32_16x16x32_bf16 v[16:19], v[128:131], v[32:35], v[16:19]
	v_mfma_f32_16x16x32_bf16 v[20:23], v[128:131], v[36:39], v[20:23]
	v_mfma_f32_16x16x32_bf16 v[24:27], v[120:123], v[32:35], v[24:27]
	v_mfma_f32_16x16x32_bf16 v[28:31], v[120:123], v[36:39], v[28:31]
	s_waitcnt lgkmcnt(0)
	v_mfma_f32_16x16x32_bf16 v[16:19], v[132:135], v[40:43], v[16:19]
	v_mfma_f32_16x16x32_bf16 v[20:23], v[132:135], v[44:47], v[20:23]
	s_nop 7
	v_cvt_pk_bf16_f32 v64, v16, v17
	v_cvt_pk_bf16_f32 v65, v18, v19
	v_cvt_pk_bf16_f32 v66, v20, v21
	v_cvt_pk_bf16_f32 v67, v22, v23
	ds_write_b64 v11, v[64:65] offset:0
	ds_write_b64 v11, v[66:67] offset:4352
	v_cvt_pk_bf16_f32 v68, v24, v25
	v_cvt_pk_bf16_f32 v69, v26, v27
	v_cvt_pk_bf16_f32 v70, v28, v29
	v_cvt_pk_bf16_f32 v71, v30, v31
	ds_write_b16 v13, v68 offset:0
	ds_write_b16_d16_hi v13, v68 offset:80
	ds_write_b16 v13, v69 offset:160
	ds_write_b16_d16_hi v13, v69 offset:240
	ds_write_b16 v13, v70 offset:32
	ds_write_b16_d16_hi v13, v70 offset:112
	ds_write_b16 v13, v71 offset:192
	ds_write_b16_d16_hi v13, v71 offset:272
	ds_read_b128 v[176:179], v172
	s_waitcnt lgkmcnt(0)
	s_barrier
	s_setprio 0
	global_store_dwordx4 v12, v[176:179], s[8:9]
	v_add_u32_e32 v12, 0x20000, v12
	s_waitcnt vmcnt(14)
	ds_read_b128 v[32:35], v8 offset:0
	ds_read_b128 v[36:39], v8 offset:4352
	ds_read_b128 v[40:43], v8 offset:64
	ds_read_b128 v[44:47], v8 offset:4416
	ds_read_b128 v[48:51], v8 offset:128
	ds_read_b128 v[52:55], v8 offset:4480
	ds_read_b128 v[56:59], v8 offset:192
	ds_read_b128 v[60:63], v8 offset:4544
	global_load_dwordx4 v[72:75], v1, s[0:1]
	global_load_dwordx4 v[76:79], v1, s[0:1] offset:1024
	s_waitcnt vmcnt(12)
	v_mul_f32_e32 v16, v186, v16
	v_mul_f32_e32 v17, v186, v17
	v_mul_f32_e32 v18, v186, v18
	v_mul_f32_e32 v19, v186, v19
	global_load_dwordx4 v[80:83], v1, s[0:1] offset:2048
	v_mul_f32_e32 v20, v186, v20
	v_mul_f32_e32 v21, v186, v21
	v_mul_f32_e32 v22, v186, v22
	v_mul_f32_e32 v23, v186, v23
	global_load_dwordx4 v[84:87], v1, s[0:1] offset:3072
	s_waitcnt lgkmcnt(6)
	v_mfma_f32_16x16x32_bf16 v[24:27], v[136:139], v[32:35], 0
	v_mfma_f32_16x16x32_bf16 v[28:31], v[136:139], v[36:39], 0
	global_load_dwordx4 v[88:91], v2, s[2:3]
	s_waitcnt lgkmcnt(4)
	v_mfma_f32_16x16x32_bf16 v[24:27], v[140:143], v[40:43], v[24:27]
	v_mfma_f32_16x16x32_bf16 v[28:31], v[140:143], v[44:47], v[28:31]
	global_load_dwordx4 v[96:99], v1, s[4:5]
	s_waitcnt lgkmcnt(2)
	v_mfma_f32_16x16x32_bf16 v[24:27], v[144:147], v[48:51], v[24:27]
	v_mfma_f32_16x16x32_bf16 v[28:31], v[144:147], v[52:55], v[28:31]
	global_load_dwordx4 v[100:103], v1, s[4:5] offset:1024
	s_waitcnt lgkmcnt(0)
	v_mfma_f32_16x16x32_bf16 v[24:27], v[148:151], v[56:59], v[24:27]
	v_mfma_f32_16x16x32_bf16 v[28:31], v[148:151], v[60:63], v[28:31]
	global_load_dword v184, v3, s[6:7]
	v_add_u32_e32 v1, 0x4000, v1
	v_add_u32_e32 v2, 0x2000, v2
	v_add_u32_e32 v3, 4, v3
	s_waitcnt lgkmcnt(0)
	s_barrier
	s_setprio 1
	ds_read_b128 v[32:35], v9 offset:17408
	ds_read_b128 v[36:39], v9 offset:19712
	ds_read_b128 v[40:43], v9 offset:17472
	ds_read_b128 v[44:47], v9 offset:19776
	s_waitcnt lgkmcnt(2)
	v_mfma_f32_16x16x32_bf16 v[16:19], v[196:199], v[32:35], v[16:19]
	v_mfma_f32_16x16x32_bf16 v[20:23], v[196:199], v[36:39], v[20:23]
	v_mfma_f32_16x16x32_bf16 v[24:27], v[188:191], v[32:35], v[24:27]
	v_mfma_f32_16x16x32_bf16 v[28:31], v[188:191], v[36:39], v[28:31]
	s_waitcnt lgkmcnt(0)
	v_mfma_f32_16x16x32_bf16 v[16:19], v[200:203], v[40:43], v[16:19]
	v_mfma_f32_16x16x32_bf16 v[20:23], v[200:203], v[44:47], v[20:23]
	s_nop 7
	v_cvt_pk_bf16_f32 v64, v16, v17
	v_cvt_pk_bf16_f32 v65, v18, v19
	v_cvt_pk_bf16_f32 v66, v20, v21
	v_cvt_pk_bf16_f32 v67, v22, v23
	ds_write_b64 v11, v[64:65] offset:8704
	ds_write_b64 v11, v[66:67] offset:13056
	v_cvt_pk_bf16_f32 v68, v24, v25
	v_cvt_pk_bf16_f32 v69, v26, v27
	v_cvt_pk_bf16_f32 v70, v28, v29
	v_cvt_pk_bf16_f32 v71, v30, v31
	ds_write_b16 v13, v68 offset:0
	ds_write_b16_d16_hi v13, v68 offset:80
	ds_write_b16 v13, v69 offset:160
	ds_write_b16_d16_hi v13, v69 offset:240
	ds_write_b16 v13, v70 offset:32
	ds_write_b16_d16_hi v13, v70 offset:112
	ds_write_b16 v13, v71 offset:192
	ds_write_b16_d16_hi v13, v71 offset:272
	ds_read_b128 v[176:179], v172
	s_waitcnt lgkmcnt(0)
	s_barrier
	s_setprio 0
	global_store_dwordx4 v12, v[176:179], s[8:9]
	v_add_u32_e32 v12, 0x20000, v12
	s_waitcnt vmcnt(14)
	ds_read_b128 v[32:35], v8 offset:8704
	ds_read_b128 v[36:39], v8 offset:13056
	ds_read_b128 v[40:43], v8 offset:8768
	ds_read_b128 v[44:47], v8 offset:13120
	ds_read_b128 v[48:51], v8 offset:8832
	ds_read_b128 v[52:55], v8 offset:13184
	ds_read_b128 v[56:59], v8 offset:8896
	ds_read_b128 v[60:63], v8 offset:13248
	global_load_dwordx4 v[104:107], v1, s[0:1]
	global_load_dwordx4 v[108:111], v1, s[0:1] offset:1024
	s_waitcnt vmcnt(12)
	v_mul_f32_e32 v16, v187, v16
	v_mul_f32_e32 v17, v187, v17
	v_mul_f32_e32 v18, v187, v18
	v_mul_f32_e32 v19, v187, v19
	global_load_dwordx4 v[112:115], v1, s[0:1] offset:2048
	v_mul_f32_e32 v20, v187, v20
	v_mul_f32_e32 v21, v187, v21
	v_mul_f32_e32 v22, v187, v22
	v_mul_f32_e32 v23, v187, v23
	global_load_dwordx4 v[116:119], v1, s[0:1] offset:3072
	s_waitcnt lgkmcnt(6)
	v_mfma_f32_16x16x32_bf16 v[24:27], v[216:219], v[32:35], 0
	v_mfma_f32_16x16x32_bf16 v[28:31], v[216:219], v[36:39], 0
	global_load_dwordx4 v[120:123], v2, s[2:3]
	s_waitcnt lgkmcnt(4)
	v_mfma_f32_16x16x32_bf16 v[24:27], v[220:223], v[40:43], v[24:27]
	v_mfma_f32_16x16x32_bf16 v[28:31], v[220:223], v[44:47], v[28:31]
	global_load_dwordx4 v[128:131], v1, s[4:5]
	s_waitcnt lgkmcnt(2)
	v_mfma_f32_16x16x32_bf16 v[24:27], v[224:227], v[48:51], v[24:27]
	v_mfma_f32_16x16x32_bf16 v[28:31], v[224:227], v[52:55], v[28:31]
	global_load_dwordx4 v[132:135], v1, s[4:5] offset:1024
	s_waitcnt lgkmcnt(0)
	v_mfma_f32_16x16x32_bf16 v[24:27], v[228:231], v[56:59], v[24:27]
	v_mfma_f32_16x16x32_bf16 v[28:31], v[228:231], v[60:63], v[28:31]
	global_load_dword v185, v3, s[6:7]
	v_add_u32_e32 v1, 0x4000, v1
	v_add_u32_e32 v2, 0x2000, v2
	v_add_u32_e32 v3, 4, v3
	s_waitcnt lgkmcnt(0)
	s_barrier
	s_setprio 1
	ds_read_b128 v[32:35], v9 offset:17408
	ds_read_b128 v[36:39], v9 offset:19712
	ds_read_b128 v[40:43], v9 offset:17472
	ds_read_b128 v[44:47], v9 offset:19776
	s_waitcnt lgkmcnt(2)
	v_mfma_f32_16x16x32_bf16 v[16:19], v[240:243], v[32:35], v[16:19]
	v_mfma_f32_16x16x32_bf16 v[20:23], v[240:243], v[36:39], v[20:23]
	v_mfma_f32_16x16x32_bf16 v[24:27], v[232:235], v[32:35], v[24:27]
	v_mfma_f32_16x16x32_bf16 v[28:31], v[232:235], v[36:39], v[28:31]
	s_waitcnt lgkmcnt(0)
	v_mfma_f32_16x16x32_bf16 v[16:19], v[244:247], v[40:43], v[16:19]
	v_mfma_f32_16x16x32_bf16 v[20:23], v[244:247], v[44:47], v[20:23]
	s_nop 7
	v_cvt_pk_bf16_f32 v64, v16, v17
	v_cvt_pk_bf16_f32 v65, v18, v19
	v_cvt_pk_bf16_f32 v66, v20, v21
	v_cvt_pk_bf16_f32 v67, v22, v23
	ds_write_b64 v11, v[64:65] offset:0
	ds_write_b64 v11, v[66:67] offset:4352
	v_cvt_pk_bf16_f32 v68, v24, v25
	v_cvt_pk_bf16_f32 v69, v26, v27
	v_cvt_pk_bf16_f32 v70, v28, v29
	v_cvt_pk_bf16_f32 v71, v30, v31
	ds_write_b16 v13, v68 offset:0
	ds_write_b16_d16_hi v13, v68 offset:80
	ds_write_b16 v13, v69 offset:160
	ds_write_b16_d16_hi v13, v69 offset:240
	ds_write_b16 v13, v70 offset:32
	ds_write_b16_d16_hi v13, v70 offset:112
	ds_write_b16 v13, v71 offset:192
	ds_write_b16_d16_hi v13, v71 offset:272
	ds_read_b128 v[176:179], v172
	s_waitcnt lgkmcnt(0)
	s_barrier
	s_setprio 0
	global_store_dwordx4 v12, v[176:179], s[8:9]
	v_add_u32_e32 v12, 0x20000, v12
	s_sub_u32 s10, s10, 1
	s_cmp_lg_u32 s10, 0
	s_cbranch_scc1 .Lscan_P_loop
